# v15 stack plus sample-unit QK latent part: fragments fetched 3 k-steps ahead through a 12-buffer ring
# speedup vs baseline: 1.0105x; 1.0039x over previous
.LBB0_750:
	s_cmp_eq_u32 s24, 0x20000
	s_cselect_b64 vcc, -1, 0
	ds_read_b128 v[2:5], v187
	ds_read_b128 v[6:9], v187 offset:20480
	ds_read_b128 v[10:13], v188
	ds_read_b128 v[194:197], v189
	ds_read_b128 v[212:215], v189 offset:20480
	ds_read_b128 v[216:219], v188 offset:32
	ds_read_b128 v[220:223], v190
	ds_read_b128 v[228:231], v190 offset:20480
	ds_read_b128 v[232:235], v188 offset:64
	ds_read_b128 v[236:239], v191
	ds_read_b128 v[240:243], v191 offset:20480
	ds_read_b128 v[244:247], v188 offset:96
	s_waitcnt lgkmcnt(9)
	v_mfma_f32_32x32x16_bf16 v[96:111], v[2:5], v[10:13], 0
	v_mfma_f32_32x32x16_bf16 v[80:95], v[6:9], v[10:13], 0
	ds_read_b128 v[2:5], v187 offset:128
	ds_read_b128 v[6:9], v187 offset:20608
	ds_read_b128 v[10:13], v188 offset:128
	s_waitcnt lgkmcnt(9)
	v_mfma_f32_32x32x16_bf16 v[96:111], v[194:197], v[216:219], v[96:111]
	v_mfma_f32_32x32x16_bf16 v[80:95], v[212:215], v[216:219], v[80:95]
	ds_read_b128 v[194:197], v189 offset:128
	ds_read_b128 v[212:215], v189 offset:20608
	ds_read_b128 v[216:219], v188 offset:160
	s_waitcnt lgkmcnt(9)
	v_mfma_f32_32x32x16_bf16 v[96:111], v[220:223], v[232:235], v[96:111]
	v_mfma_f32_32x32x16_bf16 v[80:95], v[228:231], v[232:235], v[80:95]
	ds_read_b128 v[220:223], v190 offset:128
	ds_read_b128 v[228:231], v190 offset:20608
	ds_read_b128 v[232:235], v188 offset:192
	s_waitcnt lgkmcnt(9)
	v_mfma_f32_32x32x16_bf16 v[96:111], v[236:239], v[244:247], v[96:111]
	v_mfma_f32_32x32x16_bf16 v[80:95], v[240:243], v[244:247], v[80:95]
	ds_read_b128 v[236:239], v191 offset:128
	ds_read_b128 v[240:243], v191 offset:20608
	ds_read_b128 v[244:247], v188 offset:224
	s_waitcnt lgkmcnt(9)
	v_mfma_f32_32x32x16_bf16 v[96:111], v[2:5], v[10:13], v[96:111]
	v_mfma_f32_32x32x16_bf16 v[80:95], v[6:9], v[10:13], v[80:95]
	ds_read_b128 v[2:5], v187 offset:256
	ds_read_b128 v[6:9], v187 offset:20736
	ds_read_b128 v[10:13], v188 offset:256
	s_waitcnt lgkmcnt(9)
	v_mfma_f32_32x32x16_bf16 v[96:111], v[194:197], v[216:219], v[96:111]
	v_mfma_f32_32x32x16_bf16 v[80:95], v[212:215], v[216:219], v[80:95]
	ds_read_b128 v[194:197], v189 offset:256
	ds_read_b128 v[212:215], v189 offset:20736
	ds_read_b128 v[216:219], v188 offset:288
	s_waitcnt lgkmcnt(9)
	v_mfma_f32_32x32x16_bf16 v[96:111], v[220:223], v[232:235], v[96:111]
	v_mfma_f32_32x32x16_bf16 v[80:95], v[228:231], v[232:235], v[80:95]
	ds_read_b128 v[220:223], v190 offset:256
	ds_read_b128 v[228:231], v190 offset:20736
	ds_read_b128 v[232:235], v188 offset:320
	s_waitcnt lgkmcnt(9)
	v_mfma_f32_32x32x16_bf16 v[96:111], v[236:239], v[244:247], v[96:111]
	v_mfma_f32_32x32x16_bf16 v[80:95], v[240:243], v[244:247], v[80:95]
	ds_read_b128 v[236:239], v191 offset:256
	ds_read_b128 v[240:243], v191 offset:20736
	ds_read_b128 v[244:247], v188 offset:352
	s_waitcnt lgkmcnt(9)
	v_mfma_f32_32x32x16_bf16 v[96:111], v[2:5], v[10:13], v[96:111]
	v_mfma_f32_32x32x16_bf16 v[80:95], v[6:9], v[10:13], v[80:95]
	ds_read_b128 v[2:5], v187 offset:384
	ds_read_b128 v[6:9], v187 offset:20864
	ds_read_b128 v[10:13], v188 offset:384
	s_waitcnt lgkmcnt(9)
	v_mfma_f32_32x32x16_bf16 v[96:111], v[194:197], v[216:219], v[96:111]
	v_mfma_f32_32x32x16_bf16 v[80:95], v[212:215], v[216:219], v[80:95]
	ds_read_b128 v[194:197], v189 offset:384
	ds_read_b128 v[212:215], v189 offset:20864
	ds_read_b128 v[216:219], v188 offset:416
	s_waitcnt lgkmcnt(9)
	v_mfma_f32_32x32x16_bf16 v[96:111], v[220:223], v[232:235], v[96:111]
	v_mfma_f32_32x32x16_bf16 v[80:95], v[228:231], v[232:235], v[80:95]
	ds_read_b128 v[220:223], v190 offset:384
	ds_read_b128 v[228:231], v190 offset:20864
	ds_read_b128 v[232:235], v188 offset:448
	s_waitcnt lgkmcnt(9)
	v_mfma_f32_32x32x16_bf16 v[96:111], v[236:239], v[244:247], v[96:111]
	v_mfma_f32_32x32x16_bf16 v[80:95], v[240:243], v[244:247], v[80:95]
	ds_read_b128 v[236:239], v191 offset:384
	ds_read_b128 v[240:243], v191 offset:20864
	ds_read_b128 v[244:247], v188 offset:480
	s_waitcnt lgkmcnt(9)
	v_mfma_f32_32x32x16_bf16 v[96:111], v[2:5], v[10:13], v[96:111]
	v_mfma_f32_32x32x16_bf16 v[80:95], v[6:9], v[10:13], v[80:95]
	s_waitcnt lgkmcnt(6)
	v_mfma_f32_32x32x16_bf16 v[96:111], v[194:197], v[216:219], v[96:111]
	v_mfma_f32_32x32x16_bf16 v[80:95], v[212:215], v[216:219], v[80:95]
	s_waitcnt lgkmcnt(3)
	v_mfma_f32_32x32x16_bf16 v[96:111], v[220:223], v[232:235], v[96:111]
	v_mfma_f32_32x32x16_bf16 v[80:95], v[228:231], v[232:235], v[80:95]
	s_waitcnt lgkmcnt(0)
	v_mfma_f32_32x32x16_bf16 v[96:111], v[236:239], v[244:247], v[96:111]
	v_mfma_f32_32x32x16_bf16 v[80:95], v[240:243], v[244:247], v[80:95]
	v_add_u32_e32 v1, 0x400, v179
	ds_read2_b32 v[10:11], v1 offset1:8
	ds_read2_b32 v[6:7], v179 offset1:8
	ds_read2_b32 v[8:9], v179 offset0:16 offset1:24
	ds_read2_b32 v[12:13], v1 offset0:16 offset1:24
	ds_read2_b32 v[14:15], v179 offset0:64 offset1:72
	ds_read2_b32 v[194:195], v1 offset0:64 offset1:72
	ds_read2_b32 v[196:197], v179 offset0:80 offset1:88
	ds_read2_b32 v[198:199], v1 offset0:80 offset1:88
	ds_read2_b32 v[200:201], v179 offset0:128 offset1:136
	ds_read2_b32 v[202:203], v1 offset0:128 offset1:136
	ds_read2_b32 v[204:205], v179 offset0:144 offset1:152
	ds_read2_b32 v[2:3], v179 offset0:208 offset1:216
	ds_read2_b32 v[4:5], v179 offset0:192 offset1:200
	ds_read2_b32 v[206:207], v1 offset0:144 offset1:152
	ds_read2_b32 v[208:209], v1 offset0:192 offset1:200
	ds_read2_b32 v[210:211], v1 offset0:208 offset1:216
	s_waitcnt lgkmcnt(4)
	v_pk_mul_f32 v[110:111], v[110:111], v[2:3]
	s_waitcnt lgkmcnt(3)
	v_pk_mul_f32 v[108:109], v[108:109], v[4:5]
	ds_read_b128 v[2:5], v187 offset:512
	v_pk_mul_f32 v[98:99], v[98:99], v[8:9]
	v_pk_mul_f32 v[96:97], v[96:97], v[6:7]
	ds_read_b128 v[6:9], v187 offset:20992
	v_pk_mul_f32 v[106:107], v[106:107], v[204:205]
	v_pk_mul_f32 v[104:105], v[104:105], v[200:201]
	v_pk_mul_f32 v[102:103], v[102:103], v[196:197]
	v_pk_mul_f32 v[100:101], v[100:101], v[14:15]
	s_waitcnt lgkmcnt(2)
	v_pk_mul_f32 v[94:95], v[94:95], v[210:211]
	v_pk_mul_f32 v[92:93], v[92:93], v[208:209]
	v_pk_mul_f32 v[90:91], v[90:91], v[206:207]
	v_pk_mul_f32 v[88:89], v[88:89], v[202:203]
	v_pk_mul_f32 v[86:87], v[86:87], v[198:199]
	v_pk_mul_f32 v[84:85], v[84:85], v[194:195]
	v_pk_mul_f32 v[82:83], v[82:83], v[12:13]
	v_pk_mul_f32 v[80:81], v[80:81], v[10:11]
	s_waitcnt lgkmcnt(1)
	v_mfma_f32_32x32x16_bf16 v[96:111], v[2:5], v[112:115], v[96:111]
	s_waitcnt lgkmcnt(0)
	v_mfma_f32_32x32x16_bf16 v[80:95], v[6:9], v[112:115], v[80:95]
	ds_read_b128 v[2:5], v189 offset:512
	ds_read_b128 v[6:9], v189 offset:20992
	s_waitcnt lgkmcnt(1)
	v_mfma_f32_32x32x16_bf16 v[96:111], v[2:5], v[116:119], v[96:111]
	s_waitcnt lgkmcnt(0)
	v_mfma_f32_32x32x16_bf16 v[80:95], v[6:9], v[116:119], v[80:95]
	ds_read_b128 v[2:5], v190 offset:20992
	ds_read_b128 v[6:9], v190 offset:512
	s_waitcnt lgkmcnt(1)
	v_mfma_f32_32x32x16_bf16 v[80:95], v[2:5], v[120:123], v[80:95]
	ds_read_b128 v[2:5], v191 offset:20992
	ds_read_b128 v[10:13], v191 offset:512
	s_waitcnt lgkmcnt(2)
	v_mfma_f32_32x32x16_bf16 v[96:111], v[6:9], v[120:123], v[96:111]
	s_waitcnt lgkmcnt(1)
	v_mfma_f32_32x32x16_bf16 v[80:95], v[2:5], v[124:127], v[80:95]
	s_waitcnt lgkmcnt(0)
	v_mfma_f32_32x32x16_bf16 v[96:111], v[10:13], v[124:127], v[96:111]
	s_nop 9
	v_cndmask_b32_e32 v15, v90, v180, vcc
	v_cndmask_b32_e32 v6, v88, v180, vcc
	v_cndmask_b32_e32 v7, v87, v180, vcc
	v_cndmask_b32_e32 v8, v86, v180, vcc
	v_cndmask_b32_e32 v9, v85, v180, vcc
	v_cndmask_b32_e32 v10, v81, v180, vcc
	v_cndmask_b32_e32 v11, v80, v180, vcc
	v_max_f32_e32 v1, v97, v97
	v_max_f32_e32 v90, v96, v96
	v_max_f32_e32 v1, v90, v1
	v_max3_f32 v1, v1, v98, v99
	v_max3_f32 v1, v1, v100, v101
	v_cndmask_b32_e32 v87, v105, v180, vcc
	v_cndmask_b32_e32 v88, v104, v180, vcc
	v_max3_f32 v1, v1, v102, v103
	v_cndmask_b32_e32 v85, v107, v180, vcc
	v_cndmask_b32_e32 v86, v106, v180, vcc
	v_max3_f32 v1, v1, v88, v87
	v_cndmask_b32_e32 v80, v109, v180, vcc
	v_cndmask_b32_e32 v81, v108, v180, vcc
	v_max3_f32 v1, v1, v86, v85
	v_cndmask_b32_e32 v12, v111, v180, vcc
	v_cndmask_b32_e32 v13, v110, v180, vcc
	v_max3_f32 v1, v1, v81, v80
	v_max3_f32 v1, v1, v13, v12
	v_cndmask_b32_e32 v83, v83, v180, vcc
	v_cndmask_b32_e32 v82, v82, v180, vcc
	v_max3_f32 v1, v1, v11, v10
	v_cndmask_b32_e32 v84, v84, v180, vcc
	v_max3_f32 v1, v1, v82, v83
	v_max3_f32 v1, v1, v84, v9
	v_cndmask_b32_e32 v89, v89, v180, vcc
	v_max3_f32 v1, v1, v8, v7
	v_cndmask_b32_e32 v14, v91, v180, vcc
	v_max3_f32 v1, v1, v6, v89
	v_cndmask_b32_e32 v4, v93, v180, vcc
	v_cndmask_b32_e32 v5, v92, v180, vcc
	v_max3_f32 v1, v1, v15, v14
	v_cndmask_b32_e32 v2, v95, v180, vcc
	v_cndmask_b32_e32 v3, v94, v180, vcc
	v_max3_f32 v1, v1, v5, v4
	v_max3_f32 v1, v1, v3, v2
	v_mov_b32_e32 v90, v1
	s_nop 1
	v_permlane32_swap_b32_e32 v1, v90
	v_max_f32_e32 v90, v90, v90
	v_max_f32_e32 v1, v1, v1
	v_max_f32_e32 v1, v1, v90
	v_sub_f32_e32 v90, v1, v170
	v_cmp_ge_f32_e32 vcc, s80, v90
	v_max_f32_e32 v91, v170, v170
	s_cmp_eq_u64 vcc, exec
	v_max_f32_e32 v91, v91, v1
	s_cselect_b64 vcc, -1, 0
	v_sub_f32_e32 v1, v170, v91
	v_cndmask_b32_e32 v170, v91, v170, vcc
	v_mul_f32_e32 v90, 0xbdd53b94, v170
	v_fmamk_f32 v91, v96, 0x3dd53b94, v90
	v_fmamk_f32 v92, v97, 0x3dd53b94, v90
	v_fmamk_f32 v93, v98, 0x3dd53b94, v90
	v_fmamk_f32 v94, v99, 0x3dd53b94, v90
	v_fmamk_f32 v95, v100, 0x3dd53b94, v90
	v_fmamk_f32 v96, v101, 0x3dd53b94, v90
	v_fmamk_f32 v97, v102, 0x3dd53b94, v90
	v_fmamk_f32 v98, v103, 0x3dd53b94, v90
	v_fmamk_f32 v88, v88, 0x3dd53b94, v90
	v_fmamk_f32 v87, v87, 0x3dd53b94, v90
	v_fmamk_f32 v86, v86, 0x3dd53b94, v90
	v_fmamk_f32 v85, v85, 0x3dd53b94, v90
	v_fmamk_f32 v81, v81, 0x3dd53b94, v90
	v_fmamk_f32 v80, v80, 0x3dd53b94, v90
	v_fmamk_f32 v13, v13, 0x3dd53b94, v90
	v_fmamk_f32 v12, v12, 0x3dd53b94, v90
	v_fmamk_f32 v11, v11, 0x3dd53b94, v90
	v_fmamk_f32 v10, v10, 0x3dd53b94, v90
	v_fmamk_f32 v82, v82, 0x3dd53b94, v90
	v_fmamk_f32 v83, v83, 0x3dd53b94, v90
	v_fmamk_f32 v84, v84, 0x3dd53b94, v90
	v_fmamk_f32 v9, v9, 0x3dd53b94, v90
	v_fmamk_f32 v8, v8, 0x3dd53b94, v90
	v_fmamk_f32 v7, v7, 0x3dd53b94, v90
	v_fmamk_f32 v6, v6, 0x3dd53b94, v90
	v_fmamk_f32 v89, v89, 0x3dd53b94, v90
	v_fmamk_f32 v15, v15, 0x3dd53b94, v90
	v_fmamk_f32 v14, v14, 0x3dd53b94, v90
	v_fmamk_f32 v5, v5, 0x3dd53b94, v90
	v_fmamk_f32 v4, v4, 0x3dd53b94, v90
	v_fmamk_f32 v3, v3, 0x3dd53b94, v90
	v_fmac_f32_e32 v90, 0x3dd53b94, v2
	v_exp_f32_e32 v2, v91
	v_exp_f32_e32 v91, v92
	v_exp_f32_e32 v92, v93
	v_exp_f32_e32 v93, v94
	v_exp_f32_e32 v94, v95
	v_exp_f32_e32 v105, v3
	v_add_f32_e32 v3, 0, v2
	v_exp_f32_e32 v95, v96
	v_add_f32_e32 v3, v91, v3
	v_exp_f32_e32 v96, v97
	v_add_f32_e32 v3, v92, v3
	v_exp_f32_e32 v97, v98
	v_add_f32_e32 v3, v93, v3
	v_exp_f32_e32 v88, v88
	v_add_f32_e32 v3, v94, v3
	v_exp_f32_e32 v87, v87
	v_add_f32_e32 v3, v95, v3
	v_exp_f32_e32 v86, v86
	v_add_f32_e32 v3, v96, v3
	v_exp_f32_e32 v85, v85
	v_add_f32_e32 v3, v97, v3
	v_exp_f32_e32 v81, v81
	v_add_f32_e32 v3, v88, v3
	v_exp_f32_e32 v80, v80
	v_add_f32_e32 v3, v87, v3
	v_exp_f32_e32 v13, v13
	v_add_f32_e32 v3, v86, v3
	v_exp_f32_e32 v98, v12
	v_add_f32_e32 v3, v85, v3
	v_exp_f32_e32 v99, v11
	v_add_f32_e32 v3, v81, v3
	v_exp_f32_e32 v100, v10
	v_add_f32_e32 v3, v80, v3
	v_exp_f32_e32 v82, v82
	v_add_f32_e32 v3, v13, v3
	v_exp_f32_e32 v83, v83
	v_add_f32_e32 v3, v98, v3
	v_exp_f32_e32 v84, v84
	v_add_f32_e32 v3, v99, v3
	v_exp_f32_e32 v9, v9
	v_add_f32_e32 v3, v100, v3
	v_exp_f32_e32 v8, v8
	v_add_f32_e32 v3, v82, v3
	v_exp_f32_e32 v7, v7
	v_add_f32_e32 v3, v83, v3
	v_exp_f32_e32 v6, v6
	v_add_f32_e32 v3, v84, v3
	v_exp_f32_e32 v89, v89
	v_add_f32_e32 v3, v9, v3
	v_exp_f32_e32 v101, v15
	v_add_f32_e32 v3, v8, v3
	v_exp_f32_e32 v102, v14
	v_add_f32_e32 v3, v7, v3
	v_exp_f32_e32 v103, v5
	v_add_f32_e32 v3, v6, v3
	v_exp_f32_e32 v104, v4
	v_add_f32_e32 v3, v89, v3
	v_add_f32_e32 v3, v101, v3
	v_mul_f32_e32 v1, 0x3dd53b94, v1
	v_exp_f32_e32 v90, v90
	v_add_f32_e32 v3, v102, v3
	v_exp_f32_e32 v1, v1
	v_add_f32_e32 v3, v103, v3
	v_add_f32_e32 v3, v104, v3
	v_add_f32_e32 v3, v105, v3
	v_add_f32_e32 v14, v90, v3
	v_cndmask_b32_e64 v1, v1, 1.0, vcc
	v_mov_b32_e32 v15, v14
	v_cvt_pk_bf16_f32 v2, v2, v91
	v_cvt_pk_bf16_f32 v3, v92, v93
	v_cvt_pk_bf16_f32 v4, v94, v95
	v_cvt_pk_bf16_f32 v5, v96, v97
	v_cvt_pk_bf16_f32 v10, v88, v87
	v_cvt_pk_bf16_f32 v11, v86, v85
	v_cvt_pk_bf16_f32 v12, v81, v80
	v_cvt_pk_bf16_f32 v13, v13, v98
	v_cvt_pk_bf16_f32 v80, v99, v100
	v_cvt_pk_bf16_f32 v81, v82, v83
	v_cvt_pk_bf16_f32 v82, v84, v9
	v_cvt_pk_bf16_f32 v83, v8, v7
	v_cvt_pk_bf16_f32 v6, v6, v89
	v_cvt_pk_bf16_f32 v7, v101, v102
	v_cvt_pk_bf16_f32 v8, v103, v104
	v_cvt_pk_bf16_f32 v9, v105, v90
	v_permlane32_swap_b32_e32 v14, v15
	v_permlane32_swap_b32_e32 v2, v4
	v_permlane32_swap_b32_e32 v3, v5
	v_permlane32_swap_b32_e32 v10, v12
	v_permlane32_swap_b32_e32 v11, v13
	v_permlane32_swap_b32_e32 v80, v82
	v_permlane32_swap_b32_e32 v81, v83
	v_permlane32_swap_b32_e32 v6, v8
	v_permlane32_swap_b32_e32 v7, v9
	v_cmp_gt_f32_e32 vcc, 1.0, v1
	s_cbranch_vccz .LBB0_754
	s_and_saveexec_b64 s[26:27], s[8:9]
	ds_write_b32 v183, v1
	s_or_b64 exec, exec, s[26:27]
	s_waitcnt lgkmcnt(0)
	v_add_u32_e32 v96, v177, v152
	ds_read_b128 v[84:87], v96 offset:96
	ds_read_b128 v[88:91], v96 offset:64
	ds_read_b128 v[92:95], v96 offset:32
	ds_read_b128 v[96:99], v96
	s_waitcnt lgkmcnt(3)
	v_pk_mul_f32 v[28:29], v[28:29], v[84:85]
	s_waitcnt lgkmcnt(2)
	v_pk_mul_f32 v[24:25], v[24:25], v[88:89]
	s_waitcnt lgkmcnt(1)
	v_pk_mul_f32 v[20:21], v[20:21], v[92:93]
	v_pk_mul_f32 v[30:31], v[30:31], v[86:87]
	v_pk_mul_f32 v[26:27], v[26:27], v[90:91]
	v_pk_mul_f32 v[22:23], v[22:23], v[94:95]
	s_waitcnt lgkmcnt(0)
	v_pk_mul_f32 v[18:19], v[18:19], v[98:99]
	v_pk_mul_f32 v[16:17], v[16:17], v[96:97]
	v_pk_mul_f32 v[44:45], v[44:45], v[84:85]
	v_pk_mul_f32 v[40:41], v[40:41], v[88:89]
	v_pk_mul_f32 v[36:37], v[36:37], v[92:93]
	v_pk_mul_f32 v[46:47], v[46:47], v[86:87]
	v_pk_mul_f32 v[42:43], v[42:43], v[90:91]
	v_pk_mul_f32 v[38:39], v[38:39], v[94:95]
	v_pk_mul_f32 v[34:35], v[34:35], v[98:99]
	v_pk_mul_f32 v[32:33], v[32:33], v[96:97]
	v_pk_mul_f32 v[60:61], v[60:61], v[84:85]
	v_pk_mul_f32 v[56:57], v[56:57], v[88:89]
	v_pk_mul_f32 v[52:53], v[52:53], v[92:93]
	v_pk_mul_f32 v[62:63], v[62:63], v[86:87]
	v_pk_mul_f32 v[58:59], v[58:59], v[90:91]
	v_pk_mul_f32 v[54:55], v[54:55], v[94:95]
	v_pk_mul_f32 v[50:51], v[50:51], v[98:99]
	v_pk_mul_f32 v[48:49], v[48:49], v[96:97]
	v_pk_mul_f32 v[76:77], v[76:77], v[84:85]
	v_pk_mul_f32 v[72:73], v[72:73], v[88:89]
	v_pk_mul_f32 v[68:69], v[68:69], v[92:93]
	v_pk_mul_f32 v[78:79], v[78:79], v[86:87]
	v_pk_mul_f32 v[74:75], v[74:75], v[90:91]
	v_pk_mul_f32 v[70:71], v[70:71], v[94:95]
	v_pk_mul_f32 v[66:67], v[66:67], v[98:99]
	v_pk_mul_f32 v[64:65], v[64:65], v[96:97]
